# phase 5 banded tiles: the 16 x loads of the tile epilogue are issued inside K stage 14 (after the last DMA pieces) so their latency overlaps the last two stages; stale epilogue waits removed
# speedup vs baseline: 1.1360x; 1.0092x over previous
.LBB0_853:
	s_lshl_b32 s8, s11, 7
	s_ashr_i32 s9, s8, 31
	s_lshl_b64 s[18:19], s[8:9], 10
	s_waitcnt lgkmcnt(0)
	v_lshl_add_u64 v[2:3], v[98:99], 0, s[18:19]
	v_add_co_u32_e32 v4, vcc, s23, v2
	s_lshl_b32 s10, s10, 7
	s_nop 0
	v_addc_co_u32_e32 v5, vcc, 0, v3, vcc
	v_add_co_u32_e32 v6, vcc, s24, v2
	s_ashr_i32 s11, s10, 31
	s_nop 0
	v_addc_co_u32_e32 v7, vcc, 0, v3, vcc
	s_lshl_b64 s[16:17], s[10:11], 11
	s_cmp_lt_i32 s8, s29
	s_cbranch_scc0 .Ldqx_s
	v_readlane_b32 s34, v237, 3
	v_readlane_b32 s35, v237, 4
	s_mov_b32 s36, s8
	s_branch .Ldqx_j
.Ldqx_s:
	v_readlane_b32 s34, v237, 5
	v_readlane_b32 s35, v237, 6
	s_sub_i32 s36, s8, s29
.Ldqx_j:
	v_add_u32_e32 v232, s36, v116
	v_lshlrev_b32_e32 v232, 12, v232
	v_or_b32_e32 v233, s10, v120
	v_lshl_add_u32 v232, v233, 2, v232
	v_add_u32_e32 v233, 0x10000, v232
	v_add_u32_e32 v161, 0x20000, v232
	v_add_u32_e32 v175, 0x30000, v232
	s_barrier
	s_add_u32 m0, s98, 0x1000
	v_lshl_add_u64 v[66:67], v[4:5], 0, v[238:239]
	global_load_lds_dwordx4 v[66:67], off
	s_add_u32 m0, s98, 0x2000
	v_lshl_add_u64 v[74:75], v[6:7], 0, v[238:239]
	global_load_lds_dwordx4 v[74:75], off
	v_add_co_u32_e32 v4, vcc, s25, v2
	v_lshl_add_u64 v[112:113], v[102:103], 0, s[16:17]
	s_nop 0
	v_addc_co_u32_e32 v5, vcc, 0, v3, vcc
	s_mov_b32 m0, s98
	v_lshl_add_u64 v[70:71], v[2:3], 0, v[238:239]
	global_load_lds_dwordx4 v[70:71], off
	s_add_u32 m0, s98, 0x4000
	v_lshl_add_u64 v[82:83], v[112:113], 0, v[238:239]
	global_load_lds_dwordx4 v[82:83], off
	v_add_co_u32_e32 v2, vcc, s24, v112
	v_mov_b32_e32 v46, 0
	s_nop 0
	v_addc_co_u32_e32 v3, vcc, 0, v113, vcc
	s_add_u32 m0, s98, 0x3000
	v_lshl_add_u64 v[78:79], v[4:5], 0, v[238:239]
	global_load_lds_dwordx4 v[78:79], off
	s_add_u32 m0, s98, 0x5000
	v_lshl_add_u64 v[86:87], v[2:3], 0, v[238:239]
	global_load_lds_dwordx4 v[86:87], off
	v_add_co_u32_e32 v2, vcc, s26, v112
	s_mov_b32 s31, 0
	s_nop 0
	v_addc_co_u32_e32 v3, vcc, 0, v113, vcc
	v_add_co_u32_e32 v4, vcc, s27, v112
	s_mov_b64 s[12:13], 0
	s_nop 0
	v_addc_co_u32_e32 v5, vcc, 0, v113, vcc
	s_add_u32 m0, s98, 0x6000
	v_lshl_add_u64 v[90:91], v[2:3], 0, v[238:239]
	global_load_lds_dwordx4 v[90:91], off
	s_add_u32 m0, s98, 0x7000
	v_lshl_add_u64 v[94:95], v[4:5], 0, v[238:239]
	global_load_lds_dwordx4 v[94:95], off
	s_mov_b32 s11, 0
	v_mov_b32_e32 v47, v46
	v_mov_b32_e32 v48, v46
	v_mov_b32_e32 v49, v46
	v_mov_b32_e32 v58, v46
	v_mov_b32_e32 v59, v46
	v_mov_b32_e32 v60, v46
	v_mov_b32_e32 v61, v46
	v_mov_b32_e32 v62, v46
	v_mov_b32_e32 v63, v46
	v_mov_b32_e32 v64, v46
	v_mov_b32_e32 v65, v46
	v_mov_b32_e32 v54, v46
	v_mov_b32_e32 v55, v46
	v_mov_b32_e32 v56, v46
	v_mov_b32_e32 v57, v46
	v_mov_b32_e32 v14, v46
	v_mov_b32_e32 v15, v46
	v_mov_b32_e32 v16, v46
	v_mov_b32_e32 v17, v46
	v_mov_b32_e32 v6, v46
	v_mov_b32_e32 v7, v46
	v_mov_b32_e32 v8, v46
	v_mov_b32_e32 v9, v46
	v_mov_b32_e32 v10, v46
	v_mov_b32_e32 v11, v46
	s_lshl_b64 s[14:15], s[8:9], 9
	v_lshl_add_u64 v[108:109], v[104:105], 0, s[18:19]
	v_lshl_add_u64 v[110:111], v[106:107], 0, s[16:17]
	v_mov_b32_e32 v12, v46
	v_mov_b32_e32 v13, v46
	v_mov_b32_e32 v50, v46
	v_mov_b32_e32 v51, v46
	v_mov_b32_e32 v52, v46
	v_mov_b32_e32 v53, v46
	v_mov_b32_e32 v42, v46
	v_mov_b32_e32 v43, v46
	v_mov_b32_e32 v44, v46
	v_mov_b32_e32 v45, v46
	v_mov_b32_e32 v30, v46
	v_mov_b32_e32 v31, v46
	v_mov_b32_e32 v32, v46
	v_mov_b32_e32 v33, v46
	v_mov_b32_e32 v34, v46
	v_mov_b32_e32 v35, v46
	v_mov_b32_e32 v36, v46
	v_mov_b32_e32 v37, v46
	v_mov_b32_e32 v38, v46
	v_mov_b32_e32 v39, v46
	v_mov_b32_e32 v40, v46
	v_mov_b32_e32 v41, v46
	v_mov_b32_e32 v26, v46
	v_mov_b32_e32 v27, v46
	v_mov_b32_e32 v28, v46
	v_mov_b32_e32 v29, v46
	v_mov_b32_e32 v22, v46
	v_mov_b32_e32 v23, v46
	v_mov_b32_e32 v24, v46
	v_mov_b32_e32 v25, v46
	v_mov_b32_e32 v18, v46
	v_mov_b32_e32 v19, v46
	v_mov_b32_e32 v20, v46
	v_mov_b32_e32 v21, v46
	v_mov_b32_e32 v2, v46
	v_mov_b32_e32 v3, v46
	v_mov_b32_e32 v4, v46
	v_mov_b32_e32 v5, v46
	s_waitcnt lgkmcnt(0)
	s_add_u32 m0, s98, 0x8000
	v_lshl_add_u64 v[70:71], v[70:71], 0, v[242:243]
	global_load_lds_dwordx4 v[70:71], off
	s_add_u32 m0, s98, 0x9000
	v_lshl_add_u64 v[66:67], v[66:67], 0, v[242:243]
	global_load_lds_dwordx4 v[66:67], off
	s_add_u32 m0, s98, 0xa000
	v_lshl_add_u64 v[74:75], v[74:75], 0, v[242:243]
	global_load_lds_dwordx4 v[74:75], off
	s_add_u32 m0, s98, 0xb000
	v_lshl_add_u64 v[78:79], v[78:79], 0, v[242:243]
	global_load_lds_dwordx4 v[78:79], off
	s_mov_b32 s100, 0
	s_mov_b32 s101, 0x4000
	s_waitcnt vmcnt(4)
	s_barrier
	s_branch .LBB0_855

.Ldqs_4:
	s_cmp_gt_u32 s11, 14
	s_cbranch_scc1 .Ldqv_4
	s_waitcnt vmcnt(4)
	s_branch .Ldqx_4
.Ldqv_4:
	s_waitcnt vmcnt(16)
.Ldqx_4:
	s_cmpk_lg_i32 s12, 0x800
	s_mov_b32 s31, s9
	s_waitcnt lgkmcnt(0)
	s_barrier
	s_cbranch_scc0 .LBB0_869

.Ldq_4_4:
	s_cmp_lg_u32 s11, 14
	s_cbranch_scc1 .Ldqx_n
	global_load_dwordx4 v[176:179], v232, s[34:35]
	global_load_dwordx4 v[180:183], v232, s[34:35] offset:16
	global_load_dwordx4 v[184:187], v232, s[34:35] offset:128
	global_load_dwordx4 v[188:191], v232, s[34:35] offset:144
	global_load_dwordx4 v[192:195], v233, s[34:35]
	global_load_dwordx4 v[196:199], v233, s[34:35] offset:16
	global_load_dwordx4 v[200:203], v233, s[34:35] offset:128
	global_load_dwordx4 v[204:207], v233, s[34:35] offset:144
	global_load_dwordx4 v[208:211], v161, s[34:35]
	global_load_dwordx4 v[212:215], v161, s[34:35] offset:16
	global_load_dwordx4 v[216:219], v161, s[34:35] offset:128
	global_load_dwordx4 v[220:223], v161, s[34:35] offset:144
	global_load_dwordx4 v[224:227], v175, s[34:35]
	global_load_dwordx4 v[228:231], v175, s[34:35] offset:16
	global_load_dwordx4 v[162:165], v175, s[34:35] offset:128
	global_load_dwordx4 v[166:169], v175, s[34:35] offset:144

.LBB0_869:
	v_readlane_b32 s68, v237, 3
	v_readlane_b32 s69, v237, 4
	v_add_u32_e32 v112, s8, v116
	v_readlane_b32 s70, v237, 5
	v_readlane_b32 s71, v237, 6
	s_mov_b64 s[12:13], s[68:69]
	v_add_u32_e32 v66, 0xffffc000, v112
	v_ashrrev_i32_e32 v113, 31, v112
	v_cmp_gt_i32_e32 vcc, s29, v112
	s_mov_b64 s[14:15], s[70:71]
	v_or_b32_e32 v128, s10, v120
	v_cndmask_b32_e32 v67, 0, v113, vcc
	v_cndmask_b32_e32 v66, v66, v112, vcc
	v_mov_b32_e32 v130, s15
	v_mov_b32_e32 v131, s13
	v_mov_b32_e32 v140, s14
	v_mov_b32_e32 v142, s12
	v_ashrrev_i32_e32 v129, 31, v128
	v_cndmask_b32_e32 v69, v130, v131, vcc
	v_cndmask_b32_e32 v68, v140, v142, vcc
	v_lshlrev_b64 v[66:67], 12, v[66:67]
	v_lshl_add_u64 v[66:67], v[68:69], 0, v[66:67]
	v_lshlrev_b64 v[136:137], 2, v[128:129]
	v_lshl_add_u64 v[78:79], v[66:67], 0, v[136:137]
	s_nop 0
	v_or_b32_e32 v152, 16, v112
	v_add_u32_e32 v82, 0xffffc010, v112
	v_ashrrev_i32_e32 v153, 31, v152
	v_cmp_gt_i32_e32 vcc, s29, v152
	v_or_b32_e32 v154, 32, v112
	v_add_u32_e32 v108, 0xffffc020, v112
	v_cndmask_b32_e32 v83, 0, v153, vcc
	v_cndmask_b32_e32 v82, v82, v152, vcc
	v_cndmask_b32_e32 v85, v130, v131, vcc
	v_cndmask_b32_e32 v84, v140, v142, vcc
	v_or_b32_e32 v156, 48, v112
	v_ashrrev_i32_e32 v155, 31, v154
	v_cmp_gt_i32_e32 vcc, s29, v154
	v_add_u32_e32 v134, 0xffffc030, v112
	v_ashrrev_i32_e32 v157, 31, v156
	v_cndmask_b32_e32 v109, 0, v155, vcc
	v_cndmask_b32_e32 v108, v108, v154, vcc
	v_cndmask_b32_e32 v111, v130, v131, vcc
	v_cndmask_b32_e32 v110, v140, v142, vcc
	v_cmp_gt_i32_e32 vcc, s29, v156
	v_lshlrev_b64 v[82:83], 12, v[82:83]
	v_lshlrev_b64 v[108:109], 12, v[108:109]
	v_cndmask_b32_e32 v139, 0, v157, vcc
	v_cndmask_b32_e32 v138, v134, v156, vcc
	v_cndmask_b32_e32 v141, v130, v131, vcc
	v_cndmask_b32_e32 v140, v140, v142, vcc
	v_lshlrev_b64 v[138:139], 12, v[138:139]
	v_lshl_add_u64 v[82:83], v[84:85], 0, v[82:83]
	v_lshl_add_u64 v[108:109], v[110:111], 0, v[108:109]
	v_lshl_add_u64 v[138:139], v[140:141], 0, v[138:139]
	v_lshl_add_u64 v[94:95], v[82:83], 0, v[136:137]
	v_lshl_add_u64 v[132:133], v[108:109], 0, v[136:137]
	v_lshl_add_u64 v[148:149], v[138:139], 0, v[136:137]
	s_nop 0
	s_nop 0
	v_lshlrev_b64 v[158:159], 1, v[128:129]
	s_nop 0
	s_nop 0
	s_nop 0
	v_lshlrev_b64 v[112:113], 11, v[112:113]
	v_lshl_add_u64 v[112:113], s[54:55], 0, v[112:113]
	v_lshl_add_u64 v[112:113], v[112:113], 0, v[158:159]
	v_readlane_b32 s72, v237, 7
	v_readlane_b32 s73, v237, 8
	v_readlane_b32 s74, v237, 9
	v_readlane_b32 s75, v237, 10
	v_readlane_b32 s76, v237, 11
	v_readlane_b32 s77, v237, 12
	v_readlane_b32 s78, v237, 13
	v_readlane_b32 s79, v237, 14
	v_readlane_b32 s80, v237, 15
	v_readlane_b32 s81, v237, 16
	v_readlane_b32 s82, v237, 17
	v_readlane_b32 s83, v237, 18
	s_waitcnt vmcnt(0)
	v_mov_b32_e32 v66, v176
	v_mov_b32_e32 v67, v177
	v_mov_b32_e32 v68, v178
	v_mov_b32_e32 v69, v179
	v_mov_b32_e32 v70, v180
	v_mov_b32_e32 v71, v181
	v_mov_b32_e32 v72, v182
	v_mov_b32_e32 v73, v183
	v_mov_b32_e32 v74, v184
	v_mov_b32_e32 v75, v185
	v_mov_b32_e32 v76, v186
	v_mov_b32_e32 v77, v187
	v_mov_b32_e32 v78, v188
	v_mov_b32_e32 v79, v189
	v_mov_b32_e32 v80, v190
	v_mov_b32_e32 v81, v191
	v_mov_b32_e32 v82, v192
	v_mov_b32_e32 v83, v193
	v_mov_b32_e32 v84, v194
	v_mov_b32_e32 v85, v195
	v_mov_b32_e32 v86, v196
	v_mov_b32_e32 v87, v197
	v_mov_b32_e32 v88, v198
	v_mov_b32_e32 v89, v199
	v_mov_b32_e32 v90, v204
	v_mov_b32_e32 v91, v205
	v_mov_b32_e32 v92, v206
	v_mov_b32_e32 v93, v207
	v_mov_b32_e32 v94, v200
	v_mov_b32_e32 v95, v201
	v_mov_b32_e32 v96, v202
	v_mov_b32_e32 v97, v203
	v_mov_b32_e32 v108, v212
	v_mov_b32_e32 v109, v213
	v_mov_b32_e32 v110, v214
	v_mov_b32_e32 v111, v215
	v_mov_b32_e32 v124, v208
	v_mov_b32_e32 v125, v209
	v_mov_b32_e32 v126, v210
	v_mov_b32_e32 v127, v211
	v_mov_b32_e32 v128, v220
	v_mov_b32_e32 v129, v221
	v_mov_b32_e32 v130, v222
	v_mov_b32_e32 v131, v223
	v_mov_b32_e32 v132, v216
	v_mov_b32_e32 v133, v217
	v_mov_b32_e32 v134, v218
	v_mov_b32_e32 v135, v219
	v_mov_b32_e32 v136, v228
	v_mov_b32_e32 v137, v229
	v_mov_b32_e32 v138, v230
	v_mov_b32_e32 v139, v231
	v_mov_b32_e32 v140, v224
	v_mov_b32_e32 v141, v225
	v_mov_b32_e32 v142, v226
	v_mov_b32_e32 v143, v227
	v_mov_b32_e32 v144, v166
	v_mov_b32_e32 v145, v167
	v_mov_b32_e32 v146, v168
	v_mov_b32_e32 v147, v169
	v_mov_b32_e32 v148, v162
	v_mov_b32_e32 v149, v163
	v_mov_b32_e32 v150, v164
	v_mov_b32_e32 v151, v165
	v_pk_add_f32 v[46:47], v[46:47], v[66:67]
	s_waitcnt vmcnt(14)
	v_pk_add_f32 v[58:59], v[58:59], v[70:71]
	v_pk_add_f32 v[48:49], v[48:49], v[68:69]
	v_pk_add_f32 v[60:61], v[60:61], v[72:73]
	s_waitcnt vmcnt(13)
	v_pk_add_f32 v[68:69], v[62:63], v[74:75]
	v_pk_add_f32 v[70:71], v[64:65], v[76:77]
	v_cvt_pk_bf16_f32 v62, v46, v47
	v_pk_mul_f32 v[46:47], v[46:47], v[46:47]
	v_cvt_pk_bf16_f32 v64, v58, v59
	v_pk_mul_f32 v[58:59], v[58:59], v[58:59]
	v_cvt_pk_bf16_f32 v63, v48, v49
	v_pk_mul_f32 v[48:49], v[48:49], v[48:49]
	v_cvt_pk_bf16_f32 v65, v60, v61
	v_pk_mul_f32 v[60:61], v[60:61], v[60:61]
	v_pk_mul_f32 v[72:73], v[68:69], v[68:69]
	v_add_f32_e32 v58, v58, v59
	v_add_f32_e32 v46, v46, v47
	v_cvt_pk_bf16_f32 v67, v70, v71
	v_pk_mul_f32 v[70:71], v[70:71], v[70:71]
	v_add_f32_e32 v58, v58, v60
	v_add_f32_e32 v46, v46, v48
	v_add_f32_e32 v47, v72, v73
	s_waitcnt vmcnt(12)
	v_pk_add_f32 v[54:55], v[54:55], v[78:79]
	v_add_f32_e32 v58, v58, v61
	v_add_f32_e32 v46, v46, v49
	v_add_f32_e32 v47, v47, v70
	v_cvt_pk_bf16_f32 v66, v68, v69
	v_pk_add_f32 v[56:57], v[56:57], v[80:81]
	v_cvt_pk_bf16_f32 v68, v54, v55
	v_pk_mul_f32 v[54:55], v[54:55], v[54:55]
	v_add_f32_e32 v46, v46, v58
	v_add_f32_e32 v47, v47, v71
	v_cvt_pk_bf16_f32 v69, v56, v57
	v_pk_mul_f32 v[56:57], v[56:57], v[56:57]
	v_add_f32_e32 v46, v46, v47
	v_add_f32_e32 v47, v54, v55
	v_add_f32_e32 v47, v47, v56
	v_add_f32_e32 v47, v47, v57
	v_add_f32_e32 v160, v46, v47
	s_waitcnt vmcnt(11)
	v_pk_add_f32 v[48:49], v[16:17], v[84:85]
	v_lshlrev_b64 v[46:47], 11, v[152:153]
	v_lshl_add_u64 v[54:55], s[54:55], 0, v[46:47]
	s_waitcnt vmcnt(0)
	v_pk_add_f32 v[16:17], v[20:21], v[150:151]
	ds_bpermute_b32 v20, v121, v160
	v_lshl_add_u64 v[152:153], v[54:55], 0, v[158:159]
	v_pk_add_f32 v[54:55], v[6:7], v[86:87]
	v_lshlrev_b64 v[6:7], 11, v[154:155]
	v_lshl_add_u64 v[6:7], s[54:55], 0, v[6:7]
	s_waitcnt lgkmcnt(0)
	v_add_f32_e32 v20, v160, v20
	ds_bpermute_b32 v21, v122, v20
	v_lshl_add_u64 v[86:87], v[6:7], 0, v[158:159]
	v_lshlrev_b64 v[6:7], 11, v[156:157]
	v_pk_add_f32 v[46:47], v[14:15], v[82:83]
	v_pk_add_f32 v[58:59], v[10:11], v[94:95]
	v_pk_add_f32 v[34:35], v[34:35], v[132:133]
	v_pk_add_f32 v[36:37], v[36:37], v[134:135]
	v_pk_add_f32 v[38:39], v[38:39], v[128:129]
	v_pk_add_f32 v[40:41], v[40:41], v[130:131]
	v_lshl_add_u64 v[10:11], s[54:55], 0, v[6:7]
	v_pk_add_f32 v[14:15], v[18:19], v[148:149]
	v_pk_add_f32 v[2:3], v[2:3], v[144:145]
	v_pk_add_f32 v[18:19], v[4:5], v[146:147]
	v_add_u32_e32 v4, s8, v123
	v_pk_add_f32 v[56:57], v[8:9], v[88:89]
	v_pk_add_f32 v[60:61], v[12:13], v[96:97]
	v_pk_add_f32 v[50:51], v[50:51], v[90:91]
	v_pk_add_f32 v[52:53], v[52:53], v[92:93]
	v_pk_add_f32 v[42:43], v[42:43], v[124:125]
	v_pk_add_f32 v[44:45], v[44:45], v[126:127]
	v_pk_add_f32 v[30:31], v[30:31], v[108:109]
	v_pk_add_f32 v[32:33], v[32:33], v[110:111]
	v_cvt_pk_bf16_f32 v82, v34, v35
	v_cvt_pk_bf16_f32 v83, v36, v37
	v_cvt_pk_bf16_f32 v84, v38, v39
	v_cvt_pk_bf16_f32 v85, v40, v41
	v_pk_add_f32 v[6:7], v[26:27], v[140:141]
	v_pk_add_f32 v[8:9], v[28:29], v[142:143]
	v_lshl_add_u64 v[88:89], v[10:11], 0, v[158:159]
	v_pk_add_f32 v[10:11], v[22:23], v[136:137]
	v_pk_add_f32 v[12:13], v[24:25], v[138:139]
	v_cvt_pk_bf16_f32 v22, v14, v15
	v_cvt_pk_bf16_f32 v23, v16, v17
	v_cvt_pk_bf16_f32 v24, v2, v3
	v_cvt_pk_bf16_f32 v25, v18, v19
	v_ashrrev_i32_e32 v5, 31, v4
	v_cvt_pk_bf16_f32 v70, v46, v47
	v_cvt_pk_bf16_f32 v71, v48, v49
	v_cvt_pk_bf16_f32 v72, v54, v55
	v_cvt_pk_bf16_f32 v73, v56, v57
	v_cvt_pk_bf16_f32 v74, v58, v59
	v_cvt_pk_bf16_f32 v75, v60, v61
	v_cvt_pk_bf16_f32 v76, v50, v51
	v_cvt_pk_bf16_f32 v77, v52, v53
	v_cvt_pk_bf16_f32 v78, v42, v43
	v_cvt_pk_bf16_f32 v79, v44, v45
	v_cvt_pk_bf16_f32 v80, v30, v31
	v_cvt_pk_bf16_f32 v81, v32, v33
	v_cvt_pk_bf16_f32 v26, v6, v7
	v_cvt_pk_bf16_f32 v27, v8, v9
	v_cvt_pk_bf16_f32 v28, v10, v11
	v_cvt_pk_bf16_f32 v29, v12, v13
	global_store_dwordx4 v[112:113], v[62:65], off
	global_store_dwordx4 v[112:113], v[66:69], off offset:64
	global_store_dwordx4 v[152:153], v[70:73], off
	global_store_dwordx4 v[152:153], v[74:77], off offset:64
	global_store_dwordx4 v[86:87], v[78:81], off
	global_store_dwordx4 v[86:87], v[82:85], off offset:64
	global_store_dwordx4 v[88:89], v[26:29], off
	global_store_dwordx4 v[88:89], v[22:25], off offset:64
	s_and_saveexec_b64 s[8:9], s[4:5]
	s_cbranch_execz .LBB0_871
	s_waitcnt lgkmcnt(0)
	v_add_f32_e32 v22, v20, v21
	v_lshl_add_u64 v[20:21], v[4:5], 2, s[0:1]
	global_atomic_add_f32 v[20:21], v22, off
